# attention inner loop: ALiBi per-lane base kept incrementally (1 subtract per block instead of add/add/cvt/mul), two no-op canonicalising max ops removed
# speedup vs baseline: 1.0081x; 1.0081x over previous
; #define LAS __attribute__((address_space(3)))
; __device__ __forceinline__ void attn_unit(LAS unsigned char* lds, const bf16* PROJ, bf16* DA, const float* sinkl, int unit, int tid, int wid, int lane) {
;     ...
;     const int s0 = (n - 1) * 128;
; #pragma unroll
;     for (int hp = 0; hp < 2; ++hp) {
;         v4u kreg[3], vreg[3];
; #pragma unroll
;         for (int i = 0; i < 3; ++i) {
;             const int idx = tid + 512 * (3 * hp + i), c = idx >> 3, ch = idx & 7, s = s0 + c;
;             if (s >= 0 && s < SEQ) { const bf16* p = PROJ + (rowb + s) * INW + 1024 + hk * 64 + ch * 8; kreg[i] = *(const v4u*)p; vreg[i] = *(const v4u*)(p + 128); }
;             else { kreg[i] = (v4u){0u, 0u, 0u, 0u}; vreg[i] = (v4u){0u, 0u, 0u, 0u}; }
;         }
; #pragma unroll
;         for (int i = 0; i < 3; ++i) {
;             const int idx = tid + 512 * (3 * hp + i), c = idx >> 3, ch = idx & 7;
;             *(LAS v4u*)(Ks + c * KS_PITCH + ch * 8) = kreg[i];
;             LAS bf16* vp = Vt + (ch * 8) * VT_PITCH + c;
;             vp[0 * VT_PITCH] = (bf16)(vreg[i].x & 0xffffu); vp[1 * VT_PITCH] = (bf16)(vreg[i].x >> 16);
;             vp[2 * VT_PITCH] = (bf16)(vreg[i].y & 0xffffu); vp[3 * VT_PITCH] = (bf16)(vreg[i].y >> 16);
;             vp[4 * VT_PITCH] = (bf16)(vreg[i].z & 0xffffu); vp[5 * VT_PITCH] = (bf16)(vreg[i].z >> 16);
;             vp[6 * VT_PITCH] = (bf16)(vreg[i].w & 0xffffu); vp[7 * VT_PITCH] = (bf16)(vreg[i].w >> 16);
;         }
;     }
;     __syncthreads();
.LBB0_355:
	s_and_b64 vcc, exec, s[36:37]
	s_cbranch_vccz .LBB0_423
	v_lshlrev_b32_e32 v2, 3, v173
	v_ashrrev_i32_e32 v42, 3, v173
	v_readlane_b32 s13, v239, 10
	v_and_b32_e32 v41, 56, v2
	v_lshlrev_b32_e32 v38, 1, v41
	v_mov_b32_e32 v39, v66
	s_waitcnt lgkmcnt(0)
	v_readlane_b32 s6, v239, 6
	v_readlane_b32 s7, v239, 7
	v_readlane_b32 s12, v239, 9
	s_lshl_b64 s[24:25], s[70:71], 2
	v_readlane_b32 s32, v239, 11
	s_add_u32 s24, s32, s24
	v_readlane_b32 s32, v239, 12
	s_addc_u32 s25, s32, s25
	v_readlane_b32 s88, v238, 7
	v_readlane_b32 s89, v238, 8
	v_bfe_u32 v189, v173, 5, 1
	v_lshlrev_b32_e32 v192, 4, v189
	v_mov_b32_e32 v193, v66
	v_lshl_add_u64 v[192:193], s[88:89], 0, v[192:193]
	v_and_b32_e32 v189, 31, v173
	v_or_b32_e32 v189, s80, v189
	v_or_b32_e32 v189, s12, v189
	v_or_b32_e32 v189, s6, v189
	v_mad_u64_u32 v[192:193], s[88:89], v189, s82, v[192:193]
	v_mad_i32_i24 v193, s7, v201, v193
	global_load_dwordx4 v[68:71], v[192:193], off offset:1024
	global_load_dwordx4 v[72:75], v[192:193], off offset:1056
	global_load_dwordx4 v[76:79], v[192:193], off offset:1088
	global_load_dwordx4 v[80:83], v[192:193], off offset:1120
	global_load_dword v191, v66, s[24:25]
	v_readlane_b32 s72, v238, 5
	v_readlane_b32 s73, v238, 6
	s_movk_i32 s84, 0x1000
	v_add_u32_e32 v2, 0x200, v173
	v_ashrrev_i32_e32 v43, 3, v2
	v_add_u32_e32 v2, 0x400, v173
	v_ashrrev_i32_e32 v44, 3, v2
	v_add_u32_e32 v2, 0x600, v173
	v_ashrrev_i32_e32 v186, 3, v2
	v_add_u32_e32 v2, 0x800, v173
	v_ashrrev_i32_e32 v187, 3, v2
	v_add_u32_e32 v2, 0xa00, v173
	v_ashrrev_i32_e32 v188, 3, v2
	v_add_u32_e32 v189, s13, v42
	v_cmp_gt_u32_e64 s[28:29], s84, v189
	v_and_b32_e32 v189, 0xfff, v189
	v_or_b32_e32 v190, s6, v189
	v_mov_b64_e32 v[192:193], s[72:73]
	v_mad_u64_u32 v[192:193], s[88:89], v190, s82, v[192:193]
	v_mad_i32_i24 v193, s7, v201, v193
	v_lshl_add_u64 v[192:193], v[192:193], 0, v[38:39]
	global_load_dwordx4 v[26:29], v[192:193], off offset:2048
	global_load_dwordx4 v[174:177], v[192:193], off offset:2304
	v_add_u32_e32 v189, s13, v43
	v_cmp_gt_u32_e64 s[30:31], s84, v189
	v_and_b32_e32 v189, 0xfff, v189
	v_or_b32_e32 v190, s6, v189
	v_mov_b64_e32 v[192:193], s[72:73]
	v_mad_u64_u32 v[192:193], s[88:89], v190, s82, v[192:193]
	v_mad_i32_i24 v193, s7, v201, v193
	v_lshl_add_u64 v[192:193], v[192:193], 0, v[38:39]
	global_load_dwordx4 v[30:33], v[192:193], off offset:2048
	global_load_dwordx4 v[178:181], v[192:193], off offset:2304
	v_add_u32_e32 v189, s13, v44
	v_cmp_gt_u32_e64 s[34:35], s84, v189
	v_and_b32_e32 v189, 0xfff, v189
	v_or_b32_e32 v190, s6, v189
	v_mov_b64_e32 v[192:193], s[72:73]
	v_mad_u64_u32 v[192:193], s[88:89], v190, s82, v[192:193]
	v_mad_i32_i24 v193, s7, v201, v193
	v_lshl_add_u64 v[192:193], v[192:193], 0, v[38:39]
	global_load_dwordx4 v[34:37], v[192:193], off offset:2048
	global_load_dwordx4 v[182:185], v[192:193], off offset:2304
	v_add_u32_e32 v189, s13, v186
	v_cmp_gt_u32_e64 s[62:63], s84, v189
	v_and_b32_e32 v189, 0xfff, v189
	v_or_b32_e32 v190, s6, v189
	v_mov_b64_e32 v[192:193], s[72:73]
	v_mad_u64_u32 v[192:193], s[88:89], v190, s82, v[192:193]
	v_mad_i32_i24 v193, s7, v201, v193
	v_lshl_add_u64 v[192:193], v[192:193], 0, v[38:39]
	global_load_dwordx4 v[6:9], v[192:193], off offset:2048
	global_load_dwordx4 v[2:5], v[192:193], off offset:2304
	v_add_u32_e32 v189, s13, v187
	v_cmp_gt_u32_e64 s[74:75], s84, v189
	v_and_b32_e32 v189, 0xfff, v189
	v_or_b32_e32 v190, s6, v189
	v_mov_b64_e32 v[192:193], s[72:73]
	v_mad_u64_u32 v[192:193], s[88:89], v190, s82, v[192:193]
	v_mad_i32_i24 v193, s7, v201, v193
	v_lshl_add_u64 v[192:193], v[192:193], 0, v[38:39]
	global_load_dwordx4 v[14:17], v[192:193], off offset:2048
	global_load_dwordx4 v[10:13], v[192:193], off offset:2304
	v_add_u32_e32 v189, s13, v188
	v_cmp_gt_u32_e64 s[76:77], s84, v189
	v_and_b32_e32 v189, 0xfff, v189
	v_or_b32_e32 v190, s6, v189
	v_mov_b64_e32 v[192:193], s[72:73]
	v_mad_u64_u32 v[192:193], s[88:89], v190, s82, v[192:193]
	v_mad_i32_i24 v193, s7, v201, v193
	v_lshl_add_u64 v[192:193], v[192:193], 0, v[38:39]
	global_load_dwordx4 v[22:25], v[192:193], off offset:2048
	global_load_dwordx4 v[18:21], v[192:193], off offset:2304
	v_lshl_add_u32 v40, v41, 1, 0
	s_movk_i32 s32, 0x306
	v_mad_u32_u24 v41, v41, s32, v40
	v_and_b32_e32 v123, 8, v173
	v_cmp_eq_u32_e64 s[98:99], 0, v123
	v_mov_b32_e32 v136, 0x01000504
	v_mov_b32_e32 v137, 0x03020706
	v_mov_b32_e32 v138, 0x05040100
	v_cndmask_b32_e64 v136, v136, v138, s[98:99]
	v_mov_b32_e32 v138, 0x07060302
	v_cndmask_b32_e64 v137, v137, v138, s[98:99]
	v_mov_b32_e32 v138, 0xc20
	v_cndmask_b32_e64 v138, v138, 0, s[98:99]
	v_add_u32_e32 v138, v41, v138
	s_waitcnt vmcnt(11)
	v_cndmask_b32_e64 v26, 0, v26, s[28:29]
	v_cndmask_b32_e64 v27, 0, v27, s[28:29]
	v_cndmask_b32_e64 v28, 0, v28, s[28:29]
	v_cndmask_b32_e64 v29, 0, v29, s[28:29]
	v_mad_u32_u24 v121, v42, s3, v40
	ds_write_b128 v121, v[26:29]
	s_waitcnt vmcnt(10)
	v_cndmask_b32_e64 v174, 0, v174, s[28:29]
	v_cndmask_b32_e64 v175, 0, v175, s[28:29]
	v_cndmask_b32_e64 v176, 0, v176, s[28:29]
	v_cndmask_b32_e64 v177, 0, v177, s[28:29]
	v_and_b32_e32 v123, -2, v42
	v_lshl_add_u32 v122, v123, 1, v138
	s_nop 0
	v_mov_b32_dpp v124, v174 row_ror:8 row_mask:0xf bank_mask:0xf
	v_mov_b32_dpp v125, v175 row_ror:8 row_mask:0xf bank_mask:0xf
	v_mov_b32_dpp v126, v176 row_ror:8 row_mask:0xf bank_mask:0xf
	v_mov_b32_dpp v127, v177 row_ror:8 row_mask:0xf bank_mask:0xf
	v_cndmask_b32_e64 v128, v176, v174, s[98:99]
	v_cndmask_b32_e64 v129, v177, v175, s[98:99]
	v_cndmask_b32_e64 v130, v126, v124, s[98:99]
	v_cndmask_b32_e64 v131, v127, v125, s[98:99]
	v_perm_b32 v132, v130, v128, v136
	v_perm_b32 v133, v130, v128, v137
	v_perm_b32 v134, v131, v129, v136
	v_perm_b32 v135, v131, v129, v137
	ds_write_b32 v122, v132 offset:55296
	ds_write_b32 v122, v133 offset:56072
	ds_write_b32 v122, v134 offset:56848
	ds_write_b32 v122, v135 offset:57624
	s_waitcnt vmcnt(9)
; #define LAS __attribute__((address_space(3)))
; __device__ __forceinline__ void attn_unit(LAS unsigned char* lds, const bf16* PROJ, bf16* DA, const float* sinkl, int unit, int tid, int wid, int lane) {
;     ...
; #pragma unroll
;         for (int i = 0; i < 3; ++i) {
;             const int idx = tid + 512 * (3 * hp + i), c = idx >> 3, ch = idx & 7;
;             *(LAS v4u*)(Ks + c * KS_PITCH + ch * 8) = kreg[i];
;             LAS bf16* vp = Vt + (ch * 8) * VT_PITCH + c;
;             vp[0 * VT_PITCH] = (bf16)(vreg[i].x & 0xffffu); vp[1 * VT_PITCH] = (bf16)(vreg[i].x >> 16);
;             vp[2 * VT_PITCH] = (bf16)(vreg[i].y & 0xffffu); vp[3 * VT_PITCH] = (bf16)(vreg[i].y >> 16);
;             vp[4 * VT_PITCH] = (bf16)(vreg[i].z & 0xffffu); vp[5 * VT_PITCH] = (bf16)(vreg[i].z >> 16);
;             vp[6 * VT_PITCH] = (bf16)(vreg[i].w & 0xffffu); vp[7 * VT_PITCH] = (bf16)(vreg[i].w >> 16);
;         }
;     }
;     __syncthreads();
	v_cndmask_b32_e64 v30, 0, v30, s[30:31]
	v_cndmask_b32_e64 v31, 0, v31, s[30:31]
	v_cndmask_b32_e64 v32, 0, v32, s[30:31]
	v_cndmask_b32_e64 v33, 0, v33, s[30:31]
	v_mad_u32_u24 v121, v43, s3, v40
	ds_write_b128 v121, v[30:33]
	s_waitcnt vmcnt(8)
	v_cndmask_b32_e64 v178, 0, v178, s[30:31]
	v_cndmask_b32_e64 v179, 0, v179, s[30:31]
	v_cndmask_b32_e64 v180, 0, v180, s[30:31]
	v_cndmask_b32_e64 v181, 0, v181, s[30:31]
	v_and_b32_e32 v123, -2, v43
	v_lshl_add_u32 v122, v123, 1, v138
	s_nop 0
	v_mov_b32_dpp v124, v178 row_ror:8 row_mask:0xf bank_mask:0xf
	v_mov_b32_dpp v125, v179 row_ror:8 row_mask:0xf bank_mask:0xf
	v_mov_b32_dpp v126, v180 row_ror:8 row_mask:0xf bank_mask:0xf
	v_mov_b32_dpp v127, v181 row_ror:8 row_mask:0xf bank_mask:0xf
	v_cndmask_b32_e64 v128, v180, v178, s[98:99]
	v_cndmask_b32_e64 v129, v181, v179, s[98:99]
	v_cndmask_b32_e64 v130, v126, v124, s[98:99]
	v_cndmask_b32_e64 v131, v127, v125, s[98:99]
	v_perm_b32 v132, v130, v128, v136
	v_perm_b32 v133, v130, v128, v137
	v_perm_b32 v134, v131, v129, v136
	v_perm_b32 v135, v131, v129, v137
	ds_write_b32 v122, v132 offset:55296
	ds_write_b32 v122, v133 offset:56072
	ds_write_b32 v122, v134 offset:56848
	ds_write_b32 v122, v135 offset:57624
	s_waitcnt vmcnt(7)
	v_cndmask_b32_e64 v34, 0, v34, s[34:35]
	v_cndmask_b32_e64 v35, 0, v35, s[34:35]
	v_cndmask_b32_e64 v36, 0, v36, s[34:35]
	v_cndmask_b32_e64 v37, 0, v37, s[34:35]
	v_mad_u32_u24 v121, v44, s3, v40
	ds_write_b128 v121, v[34:37]
	s_waitcnt vmcnt(6)
	v_cndmask_b32_e64 v182, 0, v182, s[34:35]
	v_cndmask_b32_e64 v183, 0, v183, s[34:35]
	v_cndmask_b32_e64 v184, 0, v184, s[34:35]
	v_cndmask_b32_e64 v185, 0, v185, s[34:35]
	v_and_b32_e32 v123, -2, v44
	v_lshl_add_u32 v122, v123, 1, v138
	s_nop 0
	v_mov_b32_dpp v124, v182 row_ror:8 row_mask:0xf bank_mask:0xf
	v_mov_b32_dpp v125, v183 row_ror:8 row_mask:0xf bank_mask:0xf
	v_mov_b32_dpp v126, v184 row_ror:8 row_mask:0xf bank_mask:0xf
	v_mov_b32_dpp v127, v185 row_ror:8 row_mask:0xf bank_mask:0xf
	v_cndmask_b32_e64 v128, v184, v182, s[98:99]
	v_cndmask_b32_e64 v129, v185, v183, s[98:99]
	v_cndmask_b32_e64 v130, v126, v124, s[98:99]
	v_cndmask_b32_e64 v131, v127, v125, s[98:99]
	v_perm_b32 v132, v130, v128, v136
	v_perm_b32 v133, v130, v128, v137
	v_perm_b32 v134, v131, v129, v136
	v_perm_b32 v135, v131, v129, v137
	ds_write_b32 v122, v132 offset:55296
	ds_write_b32 v122, v133 offset:56072
	ds_write_b32 v122, v134 offset:56848
	ds_write_b32 v122, v135 offset:57624
	s_waitcnt vmcnt(5)
	v_cndmask_b32_e64 v6, 0, v6, s[62:63]
	v_cndmask_b32_e64 v7, 0, v7, s[62:63]
	v_cndmask_b32_e64 v8, 0, v8, s[62:63]
	v_cndmask_b32_e64 v9, 0, v9, s[62:63]
	v_mad_u32_u24 v121, v186, s3, v40
	ds_write_b128 v121, v[6:9]
	s_waitcnt vmcnt(4)
	v_cndmask_b32_e64 v2, 0, v2, s[62:63]
	v_cndmask_b32_e64 v3, 0, v3, s[62:63]
	v_cndmask_b32_e64 v4, 0, v4, s[62:63]
	v_cndmask_b32_e64 v5, 0, v5, s[62:63]
	v_and_b32_e32 v123, -2, v186
	v_lshl_add_u32 v122, v123, 1, v138
	s_nop 0
	v_mov_b32_dpp v124, v2 row_ror:8 row_mask:0xf bank_mask:0xf
	v_mov_b32_dpp v125, v3 row_ror:8 row_mask:0xf bank_mask:0xf
	v_mov_b32_dpp v126, v4 row_ror:8 row_mask:0xf bank_mask:0xf
	v_mov_b32_dpp v127, v5 row_ror:8 row_mask:0xf bank_mask:0xf
	v_cndmask_b32_e64 v128, v4, v2, s[98:99]
	v_cndmask_b32_e64 v129, v5, v3, s[98:99]
	v_cndmask_b32_e64 v130, v126, v124, s[98:99]
	v_cndmask_b32_e64 v131, v127, v125, s[98:99]
	v_perm_b32 v132, v130, v128, v136
	v_perm_b32 v133, v130, v128, v137
	v_perm_b32 v134, v131, v129, v136
	v_perm_b32 v135, v131, v129, v137
	ds_write_b32 v122, v132 offset:55296
	ds_write_b32 v122, v133 offset:56072
	ds_write_b32 v122, v134 offset:56848
	ds_write_b32 v122, v135 offset:57624
	s_waitcnt vmcnt(3)
	v_cndmask_b32_e64 v14, 0, v14, s[74:75]
	v_cndmask_b32_e64 v15, 0, v15, s[74:75]
	v_cndmask_b32_e64 v16, 0, v16, s[74:75]
	v_cndmask_b32_e64 v17, 0, v17, s[74:75]
	v_mad_u32_u24 v121, v187, s3, v40
	ds_write_b128 v121, v[14:17]
	s_waitcnt vmcnt(2)
	v_cndmask_b32_e64 v10, 0, v10, s[74:75]
	v_cndmask_b32_e64 v11, 0, v11, s[74:75]
	v_cndmask_b32_e64 v12, 0, v12, s[74:75]
	v_cndmask_b32_e64 v13, 0, v13, s[74:75]
	v_and_b32_e32 v123, -2, v187
	v_lshl_add_u32 v122, v123, 1, v138
	s_nop 0
	v_mov_b32_dpp v124, v10 row_ror:8 row_mask:0xf bank_mask:0xf
	v_mov_b32_dpp v125, v11 row_ror:8 row_mask:0xf bank_mask:0xf
	v_mov_b32_dpp v126, v12 row_ror:8 row_mask:0xf bank_mask:0xf
	v_mov_b32_dpp v127, v13 row_ror:8 row_mask:0xf bank_mask:0xf
	v_cndmask_b32_e64 v128, v12, v10, s[98:99]
	v_cndmask_b32_e64 v129, v13, v11, s[98:99]
	v_cndmask_b32_e64 v130, v126, v124, s[98:99]
	v_cndmask_b32_e64 v131, v127, v125, s[98:99]
	v_perm_b32 v132, v130, v128, v136
	v_perm_b32 v133, v130, v128, v137
	v_perm_b32 v134, v131, v129, v136
	v_perm_b32 v135, v131, v129, v137
	ds_write_b32 v122, v132 offset:55296
	ds_write_b32 v122, v133 offset:56072
	ds_write_b32 v122, v134 offset:56848
	ds_write_b32 v122, v135 offset:57624
	s_waitcnt vmcnt(1)
	v_cndmask_b32_e64 v22, 0, v22, s[76:77]
	v_cndmask_b32_e64 v23, 0, v23, s[76:77]
	v_cndmask_b32_e64 v24, 0, v24, s[76:77]
	v_cndmask_b32_e64 v25, 0, v25, s[76:77]
	v_mad_u32_u24 v121, v188, s3, v40
	ds_write_b128 v121, v[22:25]
	s_waitcnt vmcnt(0)
	v_cndmask_b32_e64 v18, 0, v18, s[76:77]
	v_cndmask_b32_e64 v19, 0, v19, s[76:77]
	v_cndmask_b32_e64 v20, 0, v20, s[76:77]
	v_cndmask_b32_e64 v21, 0, v21, s[76:77]
	v_and_b32_e32 v123, -2, v188
	v_lshl_add_u32 v122, v123, 1, v138
	s_nop 0
	v_mov_b32_dpp v124, v18 row_ror:8 row_mask:0xf bank_mask:0xf
	v_mov_b32_dpp v125, v19 row_ror:8 row_mask:0xf bank_mask:0xf
	v_mov_b32_dpp v126, v20 row_ror:8 row_mask:0xf bank_mask:0xf
	v_mov_b32_dpp v127, v21 row_ror:8 row_mask:0xf bank_mask:0xf
	v_cndmask_b32_e64 v128, v20, v18, s[98:99]
	v_cndmask_b32_e64 v129, v21, v19, s[98:99]
	v_cndmask_b32_e64 v130, v126, v124, s[98:99]
	v_cndmask_b32_e64 v131, v127, v125, s[98:99]
	v_perm_b32 v132, v130, v128, v136
	v_perm_b32 v133, v130, v128, v137
	v_perm_b32 v134, v131, v129, v136
	v_perm_b32 v135, v131, v129, v137
	ds_write_b32 v122, v132 offset:55296
	ds_write_b32 v122, v133 offset:56072
	ds_write_b32 v122, v134 offset:56848
	ds_write_b32 v122, v135 offset:57624
	s_waitcnt lgkmcnt(0)
	s_barrier
; #define ATT_QK(dst, cblk) do { _Pragma("unroll") for (int r = 0; r < 16; ++r) dst[r] = 0.f; \
;             _Pragma("unroll") for (int ks = 0; ks < 4; ++ks) { const bf16x8 kf = *(const LAS bf16x8*)(Ks + ((cblk) + r32) * KS_PITCH + ks * 16 + hi * 8); \
;                 dst = __builtin_amdgcn_mfma_f32_32x32x16_bf16(kf, qf[ks], dst, 0, 0, 0); } } while (0)
; __device__ __forceinline__ void attn_unit(LAS unsigned char* lds, const bf16* PROJ, bf16* DA, const float* sinkl, int unit, int tid, int wid, int lane) {
;     ...
;     const int r32 = lane & 31, hi = lane >> 5;
;     const int hq = hk * 4 + (wid >> 1);
;     const float slope2 = __builtin_amdgcn_exp2f(-(float)(hq + 1)) * LOG2E;
;     const float sink2 = sinkl[hq] * LOG2E;
;     const float NEG = -INFINITY;
;     const bool edge_n = (n == 0) || (n == 31);
; #pragma unroll 1
;     for (int sb = 0; sb < 2; ++sb) {
;         const int a0 = 64 * (wid & 1) + 32 * sb, a = a0 + r32;
;         const size_t qrow = rowb + (size_t)n * 128 + a;
;         bf16x8 qf[4];
; #pragma unroll
;         for (int ks = 0; ks < 4; ++ks) qf[ks] = *(const bf16x8*)(PROJ + qrow * INW + 512 + hq * 64 + ks * 16 + hi * 8);
;         float mrun = sink2, l = 0.f;
;         f32x16 o0, o1;
; #pragma unroll
;         for (int r = 0; r < 16; ++r) { o0[r] = 0.f; o1[r] = 0.f; }
;         const float fb0 = (float)(r32 + 128 - 4 * hi);
;         f32x16 pn;
;     ...
;         ATT_QK(pn, a0);
; #pragma unroll 1
;         for (int i = 0; i < 9; ++i) {
;             const int c0 = a0 + 32 * i;
;             f32x16 p = pn;
;             if (i < 8) ATT_QK(pn, c0 + 32);
;             const float fb = fb0 - (float)(32 * i);
;             const int sb0 = s0 + c0 + 4 * hi;
;             const float kmin = fmaxf(fb - 128.0f, (float)(-sb0)), kmax = fminf(fb + 128.0f, (float)(SEQ - 1 - sb0));
;             const float kmid = 0.5f * (kmin + kmax), khw = 0.5f * (kmax - kmin);
;             float mx = NEG;
; #pragma unroll
;             for (int r = 0; r < 16; ++r) { const float kr = (float)((r & 3) + 8 * (r >> 2)); p[r] = p[r] - slope2 * fabsf(fb - kr); }
	v_mul_f32_e32 v204, 0x00000000, v162
	v_mul_f32_e32 v205, 0x3f800000, v162
	v_mul_f32_e32 v206, 0x40000000, v162
	v_mul_f32_e32 v207, 0x40400000, v162
	v_mul_f32_e32 v208, 0x41000000, v162
	v_mul_f32_e32 v209, 0x41100000, v162
	v_mul_f32_e32 v210, 0x41200000, v162
	v_mul_f32_e32 v211, 0x41300000, v162
	v_mul_f32_e32 v212, 0x41800000, v162
	v_mul_f32_e32 v213, 0x41880000, v162
	v_mul_f32_e32 v214, 0x41900000, v162
	v_mul_f32_e32 v215, 0x41980000, v162
	v_mul_f32_e32 v216, 0x41c00000, v162
	v_mul_f32_e32 v217, 0x41c80000, v162
	v_mul_f32_e32 v218, 0x41d00000, v162
	v_mul_f32_e32 v219, 0x41d80000, v162
	v_mul_f32_e32 v220, 0x80000000, v162
	v_mul_f32_e32 v221, 0xbf800000, v162
	v_mul_f32_e32 v222, 0xc0000000, v162
	v_mul_f32_e32 v223, 0xc0400000, v162
	v_mul_f32_e32 v224, 0xc1000000, v162
	v_mul_f32_e32 v225, 0xc1100000, v162
	v_mul_f32_e32 v226, 0xc1200000, v162
	v_mul_f32_e32 v227, 0xc1300000, v162
	v_mul_f32_e32 v228, 0xc1800000, v162
	v_mul_f32_e32 v229, 0xc1880000, v162
	v_mul_f32_e32 v230, 0xc1900000, v162
	v_mul_f32_e32 v231, 0xc1980000, v162
	v_mul_f32_e32 v232, 0xc1c00000, v162
	v_mul_f32_e32 v233, 0xc1c80000, v162
	v_mul_f32_e32 v234, 0xc1d00000, v162
	v_mul_f32_e32 v235, 0xc1d80000, v162
	v_mul_f32_e32 v167, 0x42000000, v162
	v_and_b32_e32 v67, 63, v173
	v_bfe_u32 v2, v173, 5, 1
	v_readlane_b32 s24, v238, 7
	v_and_b32_e32 v85, 31, v173
	v_lshlrev_b32_e32 v4, 3, v2
	v_lshlrev_b32_e32 v5, 2, v2
	v_lshlrev_b32_e32 v2, 4, v2
	v_or_b32_e32 v6, 32, v67
	v_readlane_b32 s25, v238, 8
	v_mul_u32_u24_e32 v7, 0x308, v85
	v_mul_u32_u24_e32 v8, 0x308, v6
	v_readlane_b32 s13, v238, 15
	v_add_u32_e32 v84, 0, v2
	v_sub_u32_e32 v95, v85, v5
	v_cvt_f32_i32_e32 v147, v95
	v_cmp_ge_f32_e32 vcc, 0x00000000, v147
	s_nop 1
	v_cndmask_b32_e32 v34, v202, v204, vcc
	v_cmp_le_f32_e32 vcc, 0x00000000, v147
	s_nop 1
	v_cndmask_b32_e32 v106, v202, v220, vcc
	v_cmp_ge_f32_e32 vcc, 0x3f800000, v147
	s_nop 1
	v_cndmask_b32_e32 v35, v202, v205, vcc
	v_cmp_le_f32_e32 vcc, 0x3f800000, v147
	s_nop 1
	v_cndmask_b32_e32 v107, v202, v221, vcc
	v_cmp_ge_f32_e32 vcc, 0x40000000, v147
	s_nop 1
	v_cndmask_b32_e32 v36, v202, v206, vcc
	v_cmp_le_f32_e32 vcc, 0x40000000, v147
	s_nop 1
	v_cndmask_b32_e32 v108, v202, v222, vcc
	v_cmp_ge_f32_e32 vcc, 0x40400000, v147
	s_nop 1
	v_cndmask_b32_e32 v37, v202, v207, vcc
	v_cmp_le_f32_e32 vcc, 0x40400000, v147
	s_nop 1
	v_cndmask_b32_e32 v109, v202, v223, vcc
	v_cmp_ge_f32_e32 vcc, 0x41000000, v147
	s_nop 1
	v_cndmask_b32_e32 v38, v202, v208, vcc
	v_cmp_le_f32_e32 vcc, 0x41000000, v147
	s_nop 1
	v_cndmask_b32_e32 v110, v202, v224, vcc
	v_cmp_ge_f32_e32 vcc, 0x41100000, v147
	s_nop 1
	v_cndmask_b32_e32 v39, v202, v209, vcc
	v_cmp_le_f32_e32 vcc, 0x41100000, v147
	s_nop 1
	v_cndmask_b32_e32 v111, v202, v225, vcc
	v_cmp_ge_f32_e32 vcc, 0x41200000, v147
	s_nop 1
	v_cndmask_b32_e32 v40, v202, v210, vcc
	v_cmp_le_f32_e32 vcc, 0x41200000, v147
	s_nop 1
	v_cndmask_b32_e32 v112, v202, v226, vcc
	v_cmp_ge_f32_e32 vcc, 0x41300000, v147
	s_nop 1
	v_cndmask_b32_e32 v41, v202, v211, vcc
	v_cmp_le_f32_e32 vcc, 0x41300000, v147
	s_nop 1
	v_cndmask_b32_e32 v113, v202, v227, vcc
	v_cmp_ge_f32_e32 vcc, 0x41800000, v147
	s_nop 1
	v_cndmask_b32_e32 v42, v202, v212, vcc
	v_cmp_le_f32_e32 vcc, 0x41800000, v147
	s_nop 1
	v_cndmask_b32_e32 v114, v202, v228, vcc
	v_cmp_ge_f32_e32 vcc, 0x41880000, v147
	s_nop 1
	v_cndmask_b32_e32 v43, v202, v213, vcc
	v_cmp_le_f32_e32 vcc, 0x41880000, v147
	s_nop 1
	v_cndmask_b32_e32 v115, v202, v229, vcc
	v_cmp_ge_f32_e32 vcc, 0x41900000, v147
	s_nop 1
	v_cndmask_b32_e32 v44, v202, v214, vcc
	v_cmp_le_f32_e32 vcc, 0x41900000, v147
	s_nop 1
	v_cndmask_b32_e32 v116, v202, v230, vcc
	v_cmp_ge_f32_e32 vcc, 0x41980000, v147
	s_nop 1
	v_cndmask_b32_e32 v45, v202, v215, vcc
	v_cmp_le_f32_e32 vcc, 0x41980000, v147
	s_nop 1
	v_cndmask_b32_e32 v117, v202, v231, vcc
	v_cmp_ge_f32_e32 vcc, 0x41c00000, v147
	s_nop 1
	v_cndmask_b32_e32 v46, v202, v216, vcc
	v_cmp_le_f32_e32 vcc, 0x41c00000, v147
	s_nop 1
	v_cndmask_b32_e32 v118, v202, v232, vcc
	v_cmp_ge_f32_e32 vcc, 0x41c80000, v147
	s_nop 1
	v_cndmask_b32_e32 v47, v202, v217, vcc
	v_cmp_le_f32_e32 vcc, 0x41c80000, v147
	s_nop 1
	v_cndmask_b32_e32 v119, v202, v233, vcc
	v_cmp_ge_f32_e32 vcc, 0x41d00000, v147
	s_nop 1
	v_cndmask_b32_e32 v48, v202, v218, vcc
	v_cmp_le_f32_e32 vcc, 0x41d00000, v147
	s_nop 1
	v_cndmask_b32_e32 v120, v202, v234, vcc
	v_cmp_ge_f32_e32 vcc, 0x41d80000, v147
	s_nop 1
	v_cndmask_b32_e32 v49, v202, v219, vcc
	v_cmp_le_f32_e32 vcc, 0x41d80000, v147
	s_nop 1
	v_cndmask_b32_e32 v121, v202, v235, vcc
	v_add3_u32 v96, v8, v4, s13
	v_add3_u32 v97, v7, v4, s13
	v_readlane_b32 s13, v238, 19
	v_add_u32_e32 v99, s80, v6
	s_mov_b32 s36, 0
	v_sub_u32_e32 v98, s13, v5
	s_mov_b64 s[38:39], -1
	s_mov_b32 s23, 0
	v_mul_f32_e32 v94, 0x3fb8aa3b, v191
	v_mov_b32_e32 v3, v66
	v_lshl_add_u64 v[86:87], s[24:25], 0, v[2:3]
	v_readlane_b32 s24, v238, 9
	v_readlane_b32 s25, v238, 10
	s_nop 1
	v_lshl_add_u64 v[88:89], s[24:25], 0, v[2:3]
	s_branch .LBB0_380

; #define ATT_QK(dst, cblk) do { _Pragma("unroll") for (int r = 0; r < 16; ++r) dst[r] = 0.f; \
;             _Pragma("unroll") for (int ks = 0; ks < 4; ++ks) { const bf16x8 kf = *(const LAS bf16x8*)(Ks + ((cblk) + r32) * KS_PITCH + ks * 16 + hi * 8); \
;                 dst = __builtin_amdgcn_mfma_f32_32x32x16_bf16(kf, qf[ks], dst, 0, 0, 0); } } while (0)
; __device__ __forceinline__ void attn_unit(LAS unsigned char* lds, const bf16* PROJ, bf16* DA, const float* sinkl, int unit, int tid, int wid, int lane) {
;     ...
;         const int a0 = 64 * (wid & 1) + 32 * sb, a = a0 + r32;
;         const size_t qrow = rowb + (size_t)n * 128 + a;
;         bf16x8 qf[4];
; #pragma unroll
;         for (int ks = 0; ks < 4; ++ks) qf[ks] = *(const bf16x8*)(PROJ + qrow * INW + 512 + hq * 64 + ks * 16 + hi * 8);
;         float mrun = sink2, l = 0.f;
;         f32x16 o0, o1;
; #pragma unroll
;         for (int r = 0; r < 16; ++r) { o0[r] = 0.f; o1[r] = 0.f; }
;         const float fb0 = (float)(r32 + 128 - 4 * hi);
;         f32x16 pn;
;     ...
;         ATT_QK(pn, a0);
.Lq_skip1:
	v_mad_u32_u24 v26, v4, s3, v84
	ds_read_b128 v[18:21], v26
	ds_read_b128 v[22:25], v26 offset:32
	s_mov_b32 s37, s36
	s_xor_b64 s[70:71], s[38:39], -1
	s_mov_b32 s38, s36
	s_mov_b32 s39, s36
	s_mov_b32 s40, s36
	s_mov_b32 s41, s36
	s_mov_b32 s42, s36
	s_mov_b32 s43, s36
	s_mov_b32 s44, s36
	s_mov_b32 s45, s36
	s_mov_b32 s46, s36
	s_mov_b32 s47, s36
	s_mov_b32 s48, s36
	s_mov_b32 s49, s36
	s_mov_b32 s50, s36
	s_mov_b32 s51, s36
	v_mov_b64_e32 v[2:3], s[36:37]
	v_mov_b64_e32 v[16:17], s[50:51]
	s_lshl_b32 s24, s23, 1
	v_mov_b64_e32 v[4:5], s[38:39]
	v_mov_b64_e32 v[6:7], s[40:41]
	v_mov_b64_e32 v[8:9], s[42:43]
	v_mov_b64_e32 v[10:11], s[44:45]
	v_mov_b64_e32 v[12:13], s[46:47]
	v_mov_b64_e32 v[14:15], s[48:49]
	v_add_u32_e32 v100, s24, v96
	v_add_u32_e32 v101, s24, v97
	v_mov_b32_e32 v91, s7
	v_subrev_u32_e32 v102, s23, v98
	v_mov_b32_e32 v103, v94
	v_add_u32_e32 v166, 0x80, v95
	v_cvt_f32_i32_e32 v166, v166
	v_mul_f32_e32 v166, v162, v166
	s_waitcnt vmcnt(3) lgkmcnt(1)
	v_mfma_f32_32x32x16_bf16 v[50:65], v[18:21], v[68:71], v[34:49]
	ds_read_b128 v[18:21], v26 offset:64
	s_waitcnt vmcnt(2) lgkmcnt(1)
	v_mfma_f32_32x32x16_bf16 v[50:65], v[22:25], v[72:75], v[50:65]
	s_waitcnt vmcnt(1) lgkmcnt(0)
	v_mfma_f32_32x32x16_bf16 v[50:65], v[18:21], v[76:79], v[50:65]
	ds_read_b128 v[18:21], v26 offset:96
	s_waitcnt vmcnt(0) lgkmcnt(0)
	v_mfma_f32_32x32x16_bf16 v[50:65], v[18:21], v[80:83], v[50:65]
	v_add_u32_e32 v18, s23, v99
	v_mad_u64_u32 v[92:93], s[24:25], v18, s3, v[84:85]
	v_mov_b64_e32 v[32:33], v[16:17]
	v_mov_b32_e32 v93, 0
	s_mov_b32 s23, 0
	s_mov_b32 s24, 0
	s_nop 5
	v_mov_b64_e32 v[30:31], v[14:15]
	v_mov_b64_e32 v[28:29], v[12:13]
	v_mov_b64_e32 v[26:27], v[10:11]
	v_mov_b64_e32 v[24:25], v[8:9]
	v_mov_b64_e32 v[22:23], v[6:7]
	v_mov_b64_e32 v[20:21], v[4:5]
	v_mov_b64_e32 v[18:19], v[2:3]
	.p2align 6

; __device__ __forceinline__ void attn_unit(LAS unsigned char* lds, const bf16* PROJ, bf16* DA, const float* sinkl, int unit, int tid, int wid, int lane) {
;     ...
;             const float fb = fb0 - (float)(32 * i);
;             const int sb0 = s0 + c0 + 4 * hi;
;             const float kmin = fmaxf(fb - 128.0f, (float)(-sb0)), kmax = fminf(fb + 128.0f, (float)(SEQ - 1 - sb0));
;             const float kmid = 0.5f * (kmin + kmax), khw = 0.5f * (kmax - kmin);
;             float mx = NEG;
; #pragma unroll
;             for (int r = 0; r < 16; ++r) { const float kr = (float)((r & 3) + 8 * (r >> 2)); p[r] = p[r] - slope2 * fabsf(fb - kr); }
;             if ((i == 0) || (i == 8) || edge_n) {
; #pragma unroll
;                 for (int r = 0; r < 16; ++r) { const float kr = (float)((r & 3) + 8 * (r >> 2)); p[r] = (fabsf(kr - kmid) <= khw) ? p[r] : NEG; }
.LBB0_382:
	s_cmp_eq_u32 s23, 0xffffff80
	s_cbranch_scc1 .Lalibi_mixed
	s_cmp_gt_i32 s23, 0xffffff80
	s_cbranch_scc0 .Lalibi_neg
	v_mov_b32_e32 v146, v166
	s_branch .Lalibi_done
.Lalibi_neg:
	v_xor_b32_e32 v146, 0x80000000, v166
	s_branch .Lalibi_done
.Lalibi_mixed:
	v_add_u32_e32 v105, s23, v95
	v_add_u32_e32 v104, 0x80, v105
	v_cvt_f32_i32_e32 v104, v104
	v_fma_f32 v50, -v162, |v104|, v50
	v_subrev_f32_e32 v164, 0x3f800000, v104
	v_fma_f32 v51, -v163, |v164|, v51
	v_subrev_f32_e32 v165, 0x40000000, v104
	v_fma_f32 v52, -v162, |v165|, v52
	v_subrev_f32_e32 v164, 0x40400000, v104
	v_fma_f32 v53, -v163, |v164|, v53
	v_subrev_f32_e32 v165, 0x41000000, v104
	v_fma_f32 v54, -v162, |v165|, v54
	v_subrev_f32_e32 v164, 0x41100000, v104
	v_fma_f32 v55, -v163, |v164|, v55
	v_subrev_f32_e32 v165, 0x41200000, v104
	v_fma_f32 v56, -v162, |v165|, v56
	v_subrev_f32_e32 v164, 0x41300000, v104
	v_fma_f32 v57, -v163, |v164|, v57
	v_subrev_f32_e32 v165, 0x41800000, v104
	v_fma_f32 v58, -v162, |v165|, v58
	v_subrev_f32_e32 v164, 0x41880000, v104
	v_fma_f32 v59, -v163, |v164|, v59
	v_subrev_f32_e32 v165, 0x41900000, v104
	v_fma_f32 v60, -v162, |v165|, v60
	v_subrev_f32_e32 v164, 0x41980000, v104
	v_fma_f32 v61, -v163, |v164|, v61
	v_subrev_f32_e32 v165, 0x41c00000, v104
	v_fma_f32 v62, -v162, |v165|, v62
	v_subrev_f32_e32 v164, 0x41c80000, v104
	v_fma_f32 v63, -v163, |v164|, v63
	v_subrev_f32_e32 v165, 0x41d00000, v104
	v_fma_f32 v64, -v162, |v165|, v64
	v_subrev_f32_e32 v164, 0x41d80000, v104
	v_fma_f32 v65, -v163, |v164|, v65
	v_mov_b32_e32 v146, 0

; __device__ __forceinline__ unsigned cvt_pk_bf16(float lo, float hi) { f32x2c v = {lo, hi}; bf16x2c b = __builtin_convertvector(v, bf16x2c); return __builtin_bit_cast(unsigned, b); }
; #define LAS __attribute__((address_space(3)))
; __device__ __forceinline__ void attn_unit(LAS unsigned char* lds, const bf16* PROJ, bf16* DA, const float* sinkl, int unit, int tid, int wid, int lane) {
;     ...
; #pragma unroll
;             for (int r = 0; r < 16; ++r) mx = fmaxf(mx, p[r]);
;             { const auto rr = __builtin_amdgcn_permlane32_swap(__float_as_uint(mx), __float_as_uint(mx), false, false); mx = fmaxf(__uint_as_float(rr[0]), __uint_as_float(rr[1])); }
;             if (__any(mx > mrun + 8.0f)) {
;                 const float mnew = fmaxf(mrun, mx), alpha = __builtin_amdgcn_exp2f(mrun - mnew);
;                 mrun = mnew; l *= alpha;
; #pragma unroll
;                 for (int r = 0; r < 16; ++r) { o0[r] *= alpha; o1[r] *= alpha; }
;             }
;             float ps = 0.f;
; #pragma unroll
;             for (int r = 0; r < 16; ++r) { p[r] = __builtin_amdgcn_exp2f(p[r] - mrun); ps += p[r]; }
;             l += ps;
; #pragma unroll
;             for (int s = 0; s < 2; ++s) {
;                 v4u pw; pw.x = pg8::cvt_pk_bf16(p[8 * s + 0], p[8 * s + 1]); pw.y = pg8::cvt_pk_bf16(p[8 * s + 2], p[8 * s + 3]);
;                 pw.z = pg8::cvt_pk_bf16(p[8 * s + 4], p[8 * s + 5]); pw.w = pg8::cvt_pk_bf16(p[8 * s + 6], p[8 * s + 7]);
;                 const bf16x8 pb = __builtin_bit_cast(bf16x8, pw);
; #pragma unroll
;                 for (int db = 0; db < 2; ++db) {
;                     const LAS bf16* vp = Vt + (db * 32 + r32) * VT_PITCH + c0 + 16 * s + 4 * hi;
;                     const s16x4 vlo = *(const LAS s16x4*)vp, vhi = *(const LAS s16x4*)(vp + 8);
;                     const bf16x8 vf = (bf16x8){vlo[0], vlo[1], vlo[2], vlo[3], vhi[0], vhi[1], vhi[2], vhi[3]};
;                     if (db == 0) o0 = __builtin_amdgcn_mfma_f32_32x32x16_bf16(vf, pb, o0, 0, 0, 0);
;                     else         o1 = __builtin_amdgcn_mfma_f32_32x32x16_bf16(vf, pb, o1, 0, 0, 0);
;                 }
;             }
.LBB0_387:
	v_max3_f32 v104, v50, s22, v51
	v_max3_f32 v104, v104, v52, v53
	v_max3_f32 v104, v104, v54, v55
	v_max3_f32 v104, v104, v56, v57
	v_max3_f32 v104, v104, v58, v59
	v_max3_f32 v104, v104, v60, v61
	v_max3_f32 v104, v104, v62, v63
	v_max3_f32 v104, v104, v64, v65
	v_mov_b32_e32 v105, v104
	s_nop 1
	v_permlane32_swap_b32_e32 v104, v105
	v_max_f32_e32 v104, v104, v105
	v_sub_f32_e32 v104, v104, v146
	v_add_f32_e32 v105, 0x41000000, v103
	v_cmp_gt_f32_e32 vcc, v104, v105
	s_cbranch_vccz .LBB0_389
	v_max_f32_e32 v104, v104, v104
	v_max_f32_e32 v105, v103, v103
	v_max_f32_e32 v105, v105, v104
	v_sub_f32_e32 v103, v103, v105
	v_exp_f32_e32 v104, v103
	v_mov_b32_e32 v103, v105
	v_pk_mul_f32 v[32:33], v[32:33], v[104:105] op_sel_hi:[1,0]
	v_pk_mul_f32 v[30:31], v[30:31], v[104:105] op_sel_hi:[1,0]
	v_pk_mul_f32 v[28:29], v[28:29], v[104:105] op_sel_hi:[1,0]
	v_pk_mul_f32 v[26:27], v[26:27], v[104:105] op_sel_hi:[1,0]
	v_pk_mul_f32 v[24:25], v[24:25], v[104:105] op_sel_hi:[1,0]
	v_pk_mul_f32 v[22:23], v[22:23], v[104:105] op_sel_hi:[1,0]
	v_pk_mul_f32 v[20:21], v[20:21], v[104:105] op_sel_hi:[1,0]
	v_pk_mul_f32 v[18:19], v[18:19], v[104:105] op_sel_hi:[1,0]
	v_pk_mul_f32 v[16:17], v[16:17], v[104:105] op_sel_hi:[1,0]
	v_pk_mul_f32 v[14:15], v[14:15], v[104:105] op_sel_hi:[1,0]
	v_pk_mul_f32 v[12:13], v[12:13], v[104:105] op_sel_hi:[1,0]
	v_pk_mul_f32 v[10:11], v[10:11], v[104:105] op_sel_hi:[1,0]
	v_pk_mul_f32 v[8:9], v[8:9], v[104:105] op_sel_hi:[1,0]
	v_pk_mul_f32 v[6:7], v[6:7], v[104:105] op_sel_hi:[1,0]
	v_pk_mul_f32 v[4:5], v[4:5], v[104:105] op_sel_hi:[1,0]
	v_pk_mul_f32 v[2:3], v[2:3], v[104:105] op_sel_hi:[1,0]
	v_mul_f32_e32 v93, v93, v104
.LBB0_389:
	v_add_f32_e32 v148, v103, v146
	ds_read2_b64 v[122:125], v101 offset1:2
	ds_read2_b64 v[126:129], v100 offset1:2
	ds_read2_b64 v[130:133], v101 offset0:4 offset1:6
	ds_read2_b64 v[134:137], v100 offset0:4 offset1:6
	v_pk_add_f32 v[50:51], v[50:51], v[148:149] op_sel_hi:[1,0] neg_lo:[0,1] neg_hi:[0,1]
	v_pk_add_f32 v[52:53], v[52:53], v[148:149] op_sel_hi:[1,0] neg_lo:[0,1] neg_hi:[0,1]
	v_exp_f32_e32 v50, v50
	v_pk_add_f32 v[54:55], v[54:55], v[148:149] op_sel_hi:[1,0] neg_lo:[0,1] neg_hi:[0,1]
	v_exp_f32_e32 v51, v51
	v_pk_add_f32 v[56:57], v[56:57], v[148:149] op_sel_hi:[1,0] neg_lo:[0,1] neg_hi:[0,1]
	v_exp_f32_e32 v52, v52
	v_pk_add_f32 v[58:59], v[58:59], v[148:149] op_sel_hi:[1,0] neg_lo:[0,1] neg_hi:[0,1]
	v_exp_f32_e32 v53, v53
	v_pk_add_f32 v[60:61], v[60:61], v[148:149] op_sel_hi:[1,0] neg_lo:[0,1] neg_hi:[0,1]
	v_exp_f32_e32 v54, v54
	v_pk_add_f32 v[62:63], v[62:63], v[148:149] op_sel_hi:[1,0] neg_lo:[0,1] neg_hi:[0,1]
	v_exp_f32_e32 v55, v55
	v_pk_add_f32 v[64:65], v[64:65], v[148:149] op_sel_hi:[1,0] neg_lo:[0,1] neg_hi:[0,1]
	v_exp_f32_e32 v56, v56
	v_cvt_pk_bf16_f32 v150, v50, v51
	v_exp_f32_e32 v57, v57
	v_cvt_pk_bf16_f32 v151, v52, v53
	v_exp_f32_e32 v58, v58
	v_pk_add_f32 v[236:237], v[50:51], v[52:53]
	v_exp_f32_e32 v59, v59
	v_cvt_pk_bf16_f32 v152, v54, v55
	v_exp_f32_e32 v60, v60
	v_pk_add_f32 v[236:237], v[236:237], v[54:55]
	v_exp_f32_e32 v61, v61
	v_cvt_pk_bf16_f32 v153, v56, v57
	v_exp_f32_e32 v62, v62
	v_pk_add_f32 v[236:237], v[236:237], v[56:57]
	v_exp_f32_e32 v63, v63
	s_add_i32 s24, s24, 1
	s_sub_i32 s23, s23, 32
	s_waitcnt lgkmcnt(3)
	v_mfma_f32_32x32x16_bf16 v[18:33], v[122:125], v[150:153], v[18:33]
	v_exp_f32_e32 v64, v64
	v_cvt_pk_bf16_f32 v140, v58, v59
	v_exp_f32_e32 v65, v65
	v_cvt_pk_bf16_f32 v141, v60, v61
	v_pk_add_f32 v[236:237], v[236:237], v[58:59]
	s_waitcnt lgkmcnt(2)
	v_mfma_f32_32x32x16_bf16 v[2:17], v[126:129], v[150:153], v[2:17]
	v_cvt_pk_bf16_f32 v142, v62, v63
	v_pk_add_f32 v[236:237], v[236:237], v[60:61]
	v_cvt_pk_bf16_f32 v143, v64, v65
	v_pk_add_f32 v[236:237], v[236:237], v[62:63]
	v_pk_add_f32 v[236:237], v[236:237], v[64:65]
	v_add_u32_e32 v100, 64, v100
	s_waitcnt lgkmcnt(1)
	v_mfma_f32_32x32x16_bf16 v[18:33], v[130:133], v[140:143], v[18:33]
	v_add_u32_e32 v101, 64, v101
	v_add_f32_e32 v236, v236, v237
	s_waitcnt lgkmcnt(0)
	v_mfma_f32_32x32x16_bf16 v[2:17], v[134:137], v[140:143], v[2:17]
	v_add_f32_e32 v93, v93, v236
	v_sub_f32_e32 v166, v166, v167

; #define ATT_QK(dst, cblk) do { _Pragma("unroll") for (int r = 0; r < 16; ++r) dst[r] = 0.f; \
;             _Pragma("unroll") for (int ks = 0; ks < 4; ++ks) { const bf16x8 kf = *(const LAS bf16x8*)(Ks + ((cblk) + r32) * KS_PITCH + ks * 16 + hi * 8); \
;                 dst = __builtin_amdgcn_mfma_f32_32x32x16_bf16(kf, qf[ks], dst, 0, 0, 0); } } while (0)
; __device__ __forceinline__ void attn_unit(LAS unsigned char* lds, const bf16* PROJ, bf16* DA, const float* sinkl, int unit, int tid, int wid, int lane) {
;     ...
;         for (int i = 0; i < 9; ++i) {
;             const int c0 = a0 + 32 * i;
;             f32x16 p = pn;
;             if (i < 8) ATT_QK(pn, c0 + 32);
;             const float fb = fb0 - (float)(32 * i);
;             const int sb0 = s0 + c0 + 4 * hi;
.Lblk_skip:
	v_sub_f32_e32 v166, v166, v167
	s_add_i32 s24, s24, 1
	s_sub_i32 s23, s23, 32
	v_add_u32_e32 v100, 64, v100
	v_add_u32_e32 v101, 64, v101
	s_waitcnt lgkmcnt(0)
	s_branch .Lblk_tail
